# static s_setprio 1 for waves 4-7 across the P2 mixer phase (reset at P2 exit)
# baseline (speedup 1.0000x reference)
; #define MKCTX() Ctx C; size_t z_ = 0; { int t_ = threadIdx.x; asm volatile("" : "+s"(z_), "+v"(t_)); unsigned char* ws_ = p.ws + z_; const float* rb_ = p.in[1] + z_; \
;     C.lds = (LAS unsigned char*)lds_raw + 64; C.tid = t_; C.lane = t_ & 63; C.wave = __builtin_amdgcn_readfirstlane(t_ >> 6); C.relb = rb_; C.ws = ws_; }
; __global__ void __launch_bounds__(512) hybrid_fwd(Params p) {
;     ...
;         for (;;) {
;             MKCTX();
;             unsigned* ctl = (unsigned*)(C.ws + WS_CTL);
;             __syncthreads();
;             if (C.tid == 0) s_unit = (int)atomicAdd(ctl + 64 * (1 + l), 1u);
;             __syncthreads();
;             const int u = s_unit;
.LBB0_317:
	s_mov_b64 s[20:21], 0
	v_mov_b32_e32 v132, v229
	s_add_u32 s64, s92, s20
	s_addc_u32 s65, s93, s21
	v_readfirstlane_b32 s73, v132
	s_cmp_ge_u32 s73, 0x100
	s_cbranch_scc0 .Lprio_skip
	s_setprio 1
.Lprio_skip:
	v_cmp_eq_u32_e64 s[38:39], 0, v132
	s_barrier
	s_and_saveexec_b64 s[40:41], s[38:39]
	s_cbranch_execz .LBB0_321
	s_mov_b64 s[44:45], exec
	v_mbcnt_lo_u32_b32 v0, s44, 0
	v_mbcnt_hi_u32_b32 v0, s45, v0
	v_cmp_eq_u32_e32 vcc, 0, v0
	s_and_saveexec_b64 s[42:43], vcc
	s_cbranch_execz .LBB0_320
	s_add_u32 s20, s64, s62
	s_addc_u32 s21, s65, s63
	s_bcnt1_i32_b64 s19, s[44:45]
	v_mov_b32_e32 v1, s19
	global_atomic_add v1, v193, v1, s[20:21] offset:256 sc0

; __device__ __forceinline__ void xcd_barrier(const XcdBarrier& b) {
;     asm volatile("s_waitcnt vmcnt(0)" ::: "memory");
;     __syncthreads();
;     if (threadIdx.x == 0) {
;         unsigned* bar = b.bar;
;         __builtin_amdgcn_s_waitcnt(0);
;         unsigned nloc = b.st[0], nx = b.st[1];
;         if (nloc == 0u) { xcd_barrier_complete(bar, b.x, nloc, nx); b.st[0] = nloc; b.st[1] = nx; }
.LBB0_572:
	s_setprio 0
	s_waitcnt vmcnt(0)
	v_readlane_b32 s8, v248, 62
	v_readlane_b32 s9, v248, 63
	s_barrier
	s_and_saveexec_b64 s[38:39], s[8:9]
	v_readlane_b32 s72, v247, 3
	v_readlane_b32 s73, v247, 4
	s_mov_b64 s[74:75], 0x80000
	s_cbranch_execz .LBB0_624
	s_waitcnt vmcnt(0) expcnt(0) lgkmcnt(0)
	ds_read_b32 v2, v193 offset:16
	ds_read_b32 v0, v193 offset:20
	s_waitcnt lgkmcnt(1)
	v_cmp_ne_u32_e32 vcc, 0, v2
	s_cbranch_vccnz .LBB0_588
	s_mov_b32 s19, 1
	s_branch .LBB0_576
